# merge K-loops request the weight tile pieces before the row-tile pieces (weights come from beyond L2, row tiles hit L2)
# baseline (speedup 1.0000x reference)
; #define G_STORE(S, bf) { *(uint4*)&s->a[bf][srow][skc] = S##a0; *(uint4*)&s->a[bf][srow + 32][skc] = S##a1; \
;     if (MB == 2) { *(uint4*)&s->a[bf][srow + 64][skc] = S##a2; *(uint4*)&s->a[bf][srow + 96][skc] = S##a3; } \
;     *(uint4*)&s->b[bf][srow][skc] = S##b0; *(uint4*)&s->b[bf][srow + 32][skc] = S##b1; *(uint4*)&s->b[bf][srow + 64][skc] = S##b2; *(uint4*)&s->b[bf][srow + 96][skc] = S##b3; }
; template <int MB, bool PF2 = true>
; DI void gemm_main(const u16* __restrict__ A, int lda, const u16* __restrict__ B, int ldb, int K, f32x16 (&acc)[MB][2], GemmLds* s, int tid) {
;     ...
;   for (int kt = 0; kt < KT; kt += 2) {
;     { const int k2 = min((kt + 2) * 64, klast); G_LOAD(q, k2); }
;     __builtin_amdgcn_sched_barrier(0);
;     G_COMPUTE(0);
;     G_STORE(p, 1);
;     __syncthreads();
;     { const int k3 = min((kt + 3) * 64, klast); G_LOAD(p, k3); }
;     __builtin_amdgcn_sched_barrier(0);
;     G_COMPUTE(1);
;     G_STORE(q, 0);
;     __syncthreads();
; DI void phase_merge(const Params& p, int l, char* smem, int tid) {
;     ...
;         gemm_main<1>(p.xn + (size_t)m0 * 1024, 1024, p.WtM + (size_t)l * 4096 * 1024 + ((size_t)i * 1024 + n0) * 1024, 1024, 1024, m, s, tid);
.Lmg_seg:
	v_mov_b32_e32 v66, 0
	v_mov_b32_e32 v67, 0
	v_mov_b32_e32 v68, 0
	v_mov_b32_e32 v69, 0
	v_mov_b32_e32 v70, 0
	v_mov_b32_e32 v71, 0
	v_mov_b32_e32 v72, 0
	v_mov_b32_e32 v73, 0
	v_mov_b32_e32 v74, 0
	v_mov_b32_e32 v75, 0
	v_mov_b32_e32 v76, 0
	v_mov_b32_e32 v77, 0
	v_mov_b32_e32 v78, 0
	v_mov_b32_e32 v79, 0
	v_mov_b32_e32 v80, 0
	v_mov_b32_e32 v81, 0
	v_mov_b32_e32 v82, 0
	v_mov_b32_e32 v83, 0
	v_mov_b32_e32 v84, 0
	v_mov_b32_e32 v85, 0
	v_mov_b32_e32 v86, 0
	v_mov_b32_e32 v87, 0
	v_mov_b32_e32 v88, 0
	v_mov_b32_e32 v89, 0
	v_mov_b32_e32 v90, 0
	v_mov_b32_e32 v91, 0
	v_mov_b32_e32 v92, 0
	v_mov_b32_e32 v93, 0
	v_mov_b32_e32 v94, 0
	v_mov_b32_e32 v95, 0
	v_mov_b32_e32 v96, 0
	v_mov_b32_e32 v97, 0
	v_mov_b32_e32 v98, 0
	v_mov_b32_e32 v99, 0
	v_mov_b32_e32 v100, 0
	v_mov_b32_e32 v101, 0
	v_mov_b32_e32 v102, 0
	v_mov_b32_e32 v103, 0
	v_mov_b32_e32 v104, 0
	v_mov_b32_e32 v105, 0
	v_mov_b32_e32 v106, 0
	v_mov_b32_e32 v107, 0
	v_mov_b32_e32 v108, 0
	v_mov_b32_e32 v109, 0
	v_mov_b32_e32 v110, 0
	v_mov_b32_e32 v111, 0
	v_mov_b32_e32 v112, 0
	v_mov_b32_e32 v113, 0
	v_mov_b32_e32 v114, 0
	v_mov_b32_e32 v115, 0
	v_mov_b32_e32 v116, 0
	v_mov_b32_e32 v117, 0
	v_mov_b32_e32 v118, 0
	v_mov_b32_e32 v119, 0
	v_mov_b32_e32 v120, 0
	v_mov_b32_e32 v121, 0
	v_mov_b32_e32 v122, 0
	v_mov_b32_e32 v123, 0
	v_mov_b32_e32 v124, 0
	v_mov_b32_e32 v125, 0
	v_mov_b32_e32 v126, 0
	v_mov_b32_e32 v127, 0
	v_mov_b32_e32 v128, 0
	v_mov_b32_e32 v129, 0
	s_waitcnt vmcnt(0) lgkmcnt(0)
	s_barrier
	ds_read_b128 v[224:227], v138 offset:0
	ds_read_b128 v[232:235], v142 offset:0
	ds_read_b128 v[228:231], v138 offset:4096
	ds_read_b128 v[236:239], v142 offset:4096
	s_add_u32 m0, s10, 0xc000
	s_nop 0
	global_load_lds_dwordx4 v200, s[8:9]
	s_add_u32 m0, s10, 0xc400
	s_nop 0
	global_load_lds_dwordx4 v201, s[8:9]
	s_add_u32 m0, s10, 0xc800
	s_nop 0
	global_load_lds_dwordx4 v202, s[8:9]
	s_add_u32 m0, s10, 0xcc00
	s_nop 0
	global_load_lds_dwordx4 v203, s[8:9]
	s_add_u32 s8, s8, 128
	s_addc_u32 s9, s9, 0
	s_mov_b32 s11, 7
.Lmgm_loop:
	ds_read_b128 v[240:243], v139 offset:0
	ds_read_b128 v[192:195], v143 offset:0
	ds_read_b128 v[188:191], v139 offset:4096
	ds_read_b128 v[196:199], v143 offset:4096
	s_waitcnt lgkmcnt(4)
	s_add_u32 m0, s10, 0x8000
	v_mfma_f32_32x32x16_bf16 v[66:81], v[232:235], v[224:227], v[66:81]
	global_load_lds_dwordx4 v200, s[4:5]
	s_add_u32 m0, s10, 0x8400
	v_mfma_f32_32x32x16_bf16 v[82:97], v[236:239], v[224:227], v[82:97]
	global_load_lds_dwordx4 v201, s[4:5]
	s_add_u32 m0, s10, 0x8800
	v_mfma_f32_32x32x16_bf16 v[98:113], v[232:235], v[228:231], v[98:113]
	global_load_lds_dwordx4 v202, s[4:5]
	s_add_u32 m0, s10, 0x8c00
	v_mfma_f32_32x32x16_bf16 v[114:129], v[236:239], v[228:231], v[114:129]
	global_load_lds_dwordx4 v203, s[4:5]
	s_add_u32 s4, s4, 128
	s_addc_u32 s5, s5, 0
	ds_read_b128 v[224:227], v140 offset:0
	ds_read_b128 v[232:235], v144 offset:0
	ds_read_b128 v[228:231], v140 offset:4096
	ds_read_b128 v[236:239], v144 offset:4096
	s_waitcnt lgkmcnt(4)
	v_mfma_f32_32x32x16_bf16 v[66:81], v[192:195], v[240:243], v[66:81]
	v_mfma_f32_32x32x16_bf16 v[82:97], v[196:199], v[240:243], v[82:97]
	v_mfma_f32_32x32x16_bf16 v[98:113], v[192:195], v[188:191], v[98:113]
	v_mfma_f32_32x32x16_bf16 v[114:129], v[196:199], v[188:191], v[114:129]
	ds_read_b128 v[240:243], v141 offset:0
	ds_read_b128 v[192:195], v145 offset:0
	ds_read_b128 v[188:191], v141 offset:4096
	ds_read_b128 v[196:199], v145 offset:4096
	s_waitcnt lgkmcnt(4)
	v_mfma_f32_32x32x16_bf16 v[66:81], v[232:235], v[224:227], v[66:81]
	v_mfma_f32_32x32x16_bf16 v[82:97], v[236:239], v[224:227], v[82:97]
	v_mfma_f32_32x32x16_bf16 v[98:113], v[232:235], v[228:231], v[98:113]
	v_mfma_f32_32x32x16_bf16 v[114:129], v[236:239], v[228:231], v[114:129]
	s_waitcnt vmcnt(0) lgkmcnt(0)
	s_barrier
	ds_read_b128 v[224:227], v138 offset:32768
	ds_read_b128 v[232:235], v142 offset:32768
	ds_read_b128 v[228:231], v138 offset:36864
	ds_read_b128 v[236:239], v142 offset:36864
	s_cmp_eq_u32 s11, 0
	s_cbranch_scc1 .Lmgm_hold0
	s_add_u32 m0, s10, 0x4000
	v_mfma_f32_32x32x16_bf16 v[66:81], v[192:195], v[240:243], v[66:81]
	global_load_lds_dwordx4 v200, s[8:9]
	s_add_u32 m0, s10, 0x4400
	v_mfma_f32_32x32x16_bf16 v[82:97], v[196:199], v[240:243], v[82:97]
	global_load_lds_dwordx4 v201, s[8:9]
	s_add_u32 m0, s10, 0x4800
	v_mfma_f32_32x32x16_bf16 v[98:113], v[192:195], v[188:191], v[98:113]
	global_load_lds_dwordx4 v202, s[8:9]
	s_add_u32 m0, s10, 0x4c00
	v_mfma_f32_32x32x16_bf16 v[114:129], v[196:199], v[188:191], v[114:129]
	global_load_lds_dwordx4 v203, s[8:9]
	s_add_u32 s8, s8, 128
	s_addc_u32 s9, s9, 0
	s_branch .Lmgm_held0

; #define G_STORE(S, bf) { *(uint4*)&s->a[bf][srow][skc] = S##a0; *(uint4*)&s->a[bf][srow + 32][skc] = S##a1; \
;     if (MB == 2) { *(uint4*)&s->a[bf][srow + 64][skc] = S##a2; *(uint4*)&s->a[bf][srow + 96][skc] = S##a3; } \
;     *(uint4*)&s->b[bf][srow][skc] = S##b0; *(uint4*)&s->b[bf][srow + 32][skc] = S##b1; *(uint4*)&s->b[bf][srow + 64][skc] = S##b2; *(uint4*)&s->b[bf][srow + 96][skc] = S##b3; }
; template <int MB, bool PF2 = true>
; DI void gemm_main(const u16* __restrict__ A, int lda, const u16* __restrict__ B, int ldb, int K, f32x16 (&acc)[MB][2], GemmLds* s, int tid) {
;     ...
;   for (int kt = 0; kt < KT; kt += 2) {
;     { const int k2 = min((kt + 2) * 64, klast); G_LOAD(q, k2); }
;     __builtin_amdgcn_sched_barrier(0);
;     G_COMPUTE(0);
;     G_STORE(p, 1);
;     __syncthreads();
;     { const int k3 = min((kt + 3) * 64, klast); G_LOAD(p, k3); }
;     __builtin_amdgcn_sched_barrier(0);
;     G_COMPUTE(1);
;     G_STORE(q, 0);
;     __syncthreads();
;   }
; DI void phase_merge(const Params& p, int l, char* smem, int tid) {
;     ...
;       }
;       f32x16 t[1][2]; zero_acc<1>(t);
;       gemm_main<1>(p.G + (size_t)m0 * 1024 + i * 256, 1024, p.WtBr + ((size_t)l * 4 + i) * 1024 * 256 + (size_t)n0 * 256, 256, 256, t, s, tid);
.Lmgm_held0:
	s_cmp_eq_u32 s11, 0
	s_cbranch_scc1 .Lmgm_last
	ds_read_b128 v[240:243], v139 offset:32768
	ds_read_b128 v[192:195], v143 offset:32768
	ds_read_b128 v[188:191], v139 offset:36864
	ds_read_b128 v[196:199], v143 offset:36864
	s_waitcnt lgkmcnt(4)
	s_add_u32 m0, s10, 0x0
	v_mfma_f32_32x32x16_bf16 v[66:81], v[232:235], v[224:227], v[66:81]
	global_load_lds_dwordx4 v200, s[4:5]
	s_add_u32 m0, s10, 0x400
	v_mfma_f32_32x32x16_bf16 v[82:97], v[236:239], v[224:227], v[82:97]
	global_load_lds_dwordx4 v201, s[4:5]
	s_add_u32 m0, s10, 0x800
	v_mfma_f32_32x32x16_bf16 v[98:113], v[232:235], v[228:231], v[98:113]
	global_load_lds_dwordx4 v202, s[4:5]
	s_add_u32 m0, s10, 0xc00
	v_mfma_f32_32x32x16_bf16 v[114:129], v[236:239], v[228:231], v[114:129]
	global_load_lds_dwordx4 v203, s[4:5]
	s_add_u32 s4, s4, 128
	s_addc_u32 s5, s5, 0
	ds_read_b128 v[224:227], v140 offset:32768
	ds_read_b128 v[232:235], v144 offset:32768
	ds_read_b128 v[228:231], v140 offset:36864
	ds_read_b128 v[236:239], v144 offset:36864
	s_waitcnt lgkmcnt(4)
	v_mfma_f32_32x32x16_bf16 v[66:81], v[192:195], v[240:243], v[66:81]
	v_mfma_f32_32x32x16_bf16 v[82:97], v[196:199], v[240:243], v[82:97]
	v_mfma_f32_32x32x16_bf16 v[98:113], v[192:195], v[188:191], v[98:113]
	v_mfma_f32_32x32x16_bf16 v[114:129], v[196:199], v[188:191], v[114:129]
	ds_read_b128 v[240:243], v141 offset:32768
	ds_read_b128 v[192:195], v145 offset:32768
	ds_read_b128 v[188:191], v141 offset:36864
	ds_read_b128 v[196:199], v145 offset:36864
	s_waitcnt lgkmcnt(4)
	v_mfma_f32_32x32x16_bf16 v[66:81], v[232:235], v[224:227], v[66:81]
	v_mfma_f32_32x32x16_bf16 v[82:97], v[236:239], v[224:227], v[82:97]
	v_mfma_f32_32x32x16_bf16 v[98:113], v[232:235], v[228:231], v[98:113]
	v_mfma_f32_32x32x16_bf16 v[114:129], v[236:239], v[228:231], v[114:129]
	s_waitcnt vmcnt(0) lgkmcnt(0)
	s_barrier
	ds_read_b128 v[224:227], v138 offset:0
	ds_read_b128 v[232:235], v142 offset:0
	ds_read_b128 v[228:231], v138 offset:4096
	ds_read_b128 v[236:239], v142 offset:4096
	s_add_u32 m0, s10, 0xc000
	v_mfma_f32_32x32x16_bf16 v[66:81], v[192:195], v[240:243], v[66:81]
	global_load_lds_dwordx4 v200, s[8:9]
	s_add_u32 m0, s10, 0xc400
	v_mfma_f32_32x32x16_bf16 v[82:97], v[196:199], v[240:243], v[82:97]
	global_load_lds_dwordx4 v201, s[8:9]
	s_add_u32 m0, s10, 0xc800
	v_mfma_f32_32x32x16_bf16 v[98:113], v[192:195], v[188:191], v[98:113]
	global_load_lds_dwordx4 v202, s[8:9]
	s_add_u32 m0, s10, 0xcc00
	v_mfma_f32_32x32x16_bf16 v[114:129], v[196:199], v[188:191], v[114:129]
	global_load_lds_dwordx4 v203, s[8:9]
	s_add_u32 s8, s8, 128
	s_addc_u32 s9, s9, 0
	s_sub_u32 s11, s11, 1
	s_branch .Lmgm_loop
.Lmgm_last:
	s_lshr_b32 s6, s13, 1
	s_lshl_b32 s7, s6, 9
	s_add_u32 s4, s2, 0x16720000
	s_addc_u32 s5, s3, 0
	s_add_u32 s4, s4, s7
	s_addc_u32 s5, s5, 0
	s_lshl_b32 s7, s6, 19
	s_lshr_b32 s8, s19, 2
	s_add_u32 s7, s7, s8
	s_add_u32 s8, s16, s7
	s_addc_u32 s9, s17, 0
	ds_read_b128 v[240:243], v139 offset:32768
	ds_read_b128 v[192:195], v143 offset:32768
	ds_read_b128 v[188:191], v139 offset:36864
	ds_read_b128 v[196:199], v143 offset:36864
	s_waitcnt lgkmcnt(4)
	s_add_u32 m0, s10, 0x4000
	v_mfma_f32_32x32x16_bf16 v[66:81], v[232:235], v[224:227], v[66:81]
	global_load_lds_dwordx4 v130, s[8:9]
	s_add_u32 m0, s10, 0x4400
	v_mfma_f32_32x32x16_bf16 v[82:97], v[236:239], v[224:227], v[82:97]
	global_load_lds_dwordx4 v131, s[8:9]
	s_add_u32 m0, s10, 0x4800
	v_mfma_f32_32x32x16_bf16 v[98:113], v[232:235], v[228:231], v[98:113]
	global_load_lds_dwordx4 v132, s[8:9]
	s_add_u32 m0, s10, 0x4c00
	v_mfma_f32_32x32x16_bf16 v[114:129], v[236:239], v[228:231], v[114:129]
	global_load_lds_dwordx4 v133, s[8:9]
	s_add_u32 s8, s8, 128
	s_addc_u32 s9, s9, 0
	ds_read_b128 v[224:227], v140 offset:32768
	ds_read_b128 v[232:235], v144 offset:32768
	ds_read_b128 v[228:231], v140 offset:36864
	ds_read_b128 v[236:239], v144 offset:36864
	s_waitcnt lgkmcnt(4)
	s_add_u32 m0, s10, 0x0
	v_mfma_f32_32x32x16_bf16 v[66:81], v[192:195], v[240:243], v[66:81]
	global_load_lds_dwordx4 v200, s[4:5]
	s_add_u32 m0, s10, 0x400
	v_mfma_f32_32x32x16_bf16 v[82:97], v[196:199], v[240:243], v[82:97]
	global_load_lds_dwordx4 v201, s[4:5]
	s_add_u32 m0, s10, 0x800
	v_mfma_f32_32x32x16_bf16 v[98:113], v[192:195], v[188:191], v[98:113]
	global_load_lds_dwordx4 v202, s[4:5]
	s_add_u32 m0, s10, 0xc00
	v_mfma_f32_32x32x16_bf16 v[114:129], v[196:199], v[188:191], v[114:129]
	global_load_lds_dwordx4 v203, s[4:5]
	s_add_u32 s4, s4, 128
	s_addc_u32 s5, s5, 0
	ds_read_b128 v[240:243], v141 offset:32768
	ds_read_b128 v[192:195], v145 offset:32768
	ds_read_b128 v[188:191], v141 offset:36864
	ds_read_b128 v[196:199], v145 offset:36864
	s_waitcnt lgkmcnt(4)
	v_mfma_f32_32x32x16_bf16 v[66:81], v[232:235], v[224:227], v[66:81]
	v_mfma_f32_32x32x16_bf16 v[82:97], v[236:239], v[224:227], v[82:97]
	v_mfma_f32_32x32x16_bf16 v[98:113], v[232:235], v[228:231], v[98:113]
	v_mfma_f32_32x32x16_bf16 v[114:129], v[236:239], v[228:231], v[114:129]
	s_waitcnt lgkmcnt(0)
	s_barrier
	v_mfma_f32_32x32x16_bf16 v[66:81], v[192:195], v[240:243], v[66:81]
	v_mfma_f32_32x32x16_bf16 v[82:97], v[196:199], v[240:243], v[82:97]
	v_mfma_f32_32x32x16_bf16 v[98:113], v[192:195], v[188:191], v[98:113]
	v_mfma_f32_32x32x16_bf16 v[114:129], v[196:199], v[188:191], v[114:129]
; DI unsigned pack2(float a, float b) { f32v2 v = {a, b}; return __builtin_bit_cast(unsigned, __builtin_convertvector(v, bf16v2)); }
; DI float sigm_fast(float x) { return __builtin_amdgcn_rcpf(1.f + __expf(-x)); }
; DI void phase_merge(const Params& p, int l, char* smem, int tid) {
;     ...
; #pragma unroll
;         for (int b2 = 0; b2 < 2; b2++)
; #pragma unroll
;           for (int e = 0; e < 8; e++) sg[b2][e] = pack2(sigm_fast(m[0][b2][2 * e]), sigm_fast(m[0][b2][2 * e + 1]));
.Lmgm_kdone:
	s_nop 7
	s_nop 7
	v_mul_f32_e32 v66, 0xbfb8aa3b, v66
	v_mul_f32_e32 v67, 0xbfb8aa3b, v67
	v_mul_f32_e32 v68, 0xbfb8aa3b, v68
	v_mul_f32_e32 v69, 0xbfb8aa3b, v69
	v_mul_f32_e32 v70, 0xbfb8aa3b, v70
	v_mul_f32_e32 v71, 0xbfb8aa3b, v71
	v_mul_f32_e32 v72, 0xbfb8aa3b, v72
	v_mul_f32_e32 v73, 0xbfb8aa3b, v73
	v_exp_f32_e32 v66, v66
	v_exp_f32_e32 v67, v67
	v_exp_f32_e32 v68, v68
	v_exp_f32_e32 v69, v69
	v_exp_f32_e32 v70, v70
	v_exp_f32_e32 v71, v71
	v_exp_f32_e32 v72, v72
	v_exp_f32_e32 v73, v73
	v_add_f32_e32 v66, 1.0, v66
	v_add_f32_e32 v67, 1.0, v67
	v_add_f32_e32 v68, 1.0, v68
	v_add_f32_e32 v69, 1.0, v69
	v_add_f32_e32 v70, 1.0, v70
	v_add_f32_e32 v71, 1.0, v71
	v_add_f32_e32 v72, 1.0, v72
	v_add_f32_e32 v73, 1.0, v73
	v_rcp_f32_e32 v66, v66
	v_rcp_f32_e32 v67, v67
	v_rcp_f32_e32 v68, v68
	v_rcp_f32_e32 v69, v69
	v_rcp_f32_e32 v70, v70
	v_rcp_f32_e32 v71, v71
	v_rcp_f32_e32 v72, v72
	v_rcp_f32_e32 v73, v73
	s_nop 0
	v_cvt_pk_bf16_f32 v156, v66, v67
	v_cvt_pk_bf16_f32 v157, v68, v69
	v_cvt_pk_bf16_f32 v158, v70, v71
	v_cvt_pk_bf16_f32 v159, v72, v73
	v_mul_f32_e32 v74, 0xbfb8aa3b, v74
	v_mul_f32_e32 v75, 0xbfb8aa3b, v75
	v_mul_f32_e32 v76, 0xbfb8aa3b, v76
	v_mul_f32_e32 v77, 0xbfb8aa3b, v77
	v_mul_f32_e32 v78, 0xbfb8aa3b, v78
	v_mul_f32_e32 v79, 0xbfb8aa3b, v79
	v_mul_f32_e32 v80, 0xbfb8aa3b, v80
	v_mul_f32_e32 v81, 0xbfb8aa3b, v81
	v_exp_f32_e32 v74, v74
	v_exp_f32_e32 v75, v75
	v_exp_f32_e32 v76, v76
	v_exp_f32_e32 v77, v77
	v_exp_f32_e32 v78, v78
	v_exp_f32_e32 v79, v79
	v_exp_f32_e32 v80, v80
	v_exp_f32_e32 v81, v81
	v_add_f32_e32 v74, 1.0, v74
	v_add_f32_e32 v75, 1.0, v75
	v_add_f32_e32 v76, 1.0, v76
	v_add_f32_e32 v77, 1.0, v77
	v_add_f32_e32 v78, 1.0, v78
	v_add_f32_e32 v79, 1.0, v79
	v_add_f32_e32 v80, 1.0, v80
	v_add_f32_e32 v81, 1.0, v81
	v_rcp_f32_e32 v74, v74
	v_rcp_f32_e32 v75, v75
	v_rcp_f32_e32 v76, v76
	v_rcp_f32_e32 v77, v77
	v_rcp_f32_e32 v78, v78
	v_rcp_f32_e32 v79, v79
	v_rcp_f32_e32 v80, v80
	v_rcp_f32_e32 v81, v81
	s_nop 0
	v_cvt_pk_bf16_f32 v160, v74, v75
	v_cvt_pk_bf16_f32 v161, v76, v77
	v_cvt_pk_bf16_f32 v162, v78, v79
	v_cvt_pk_bf16_f32 v163, v80, v81
	v_mul_f32_e32 v82, 0xbfb8aa3b, v82
	v_mul_f32_e32 v83, 0xbfb8aa3b, v83
	v_mul_f32_e32 v84, 0xbfb8aa3b, v84
	v_mul_f32_e32 v85, 0xbfb8aa3b, v85
	v_mul_f32_e32 v86, 0xbfb8aa3b, v86
	v_mul_f32_e32 v87, 0xbfb8aa3b, v87
	v_mul_f32_e32 v88, 0xbfb8aa3b, v88
	v_mul_f32_e32 v89, 0xbfb8aa3b, v89
	v_exp_f32_e32 v82, v82
	v_exp_f32_e32 v83, v83
	v_exp_f32_e32 v84, v84
	v_exp_f32_e32 v85, v85
	v_exp_f32_e32 v86, v86
	v_exp_f32_e32 v87, v87
	v_exp_f32_e32 v88, v88
	v_exp_f32_e32 v89, v89
	v_add_f32_e32 v82, 1.0, v82
	v_add_f32_e32 v83, 1.0, v83
	v_add_f32_e32 v84, 1.0, v84
	v_add_f32_e32 v85, 1.0, v85
	v_add_f32_e32 v86, 1.0, v86
	v_add_f32_e32 v87, 1.0, v87
	v_add_f32_e32 v88, 1.0, v88
	v_add_f32_e32 v89, 1.0, v89
	v_rcp_f32_e32 v82, v82
	v_rcp_f32_e32 v83, v83
	v_rcp_f32_e32 v84, v84
	v_rcp_f32_e32 v85, v85
	v_rcp_f32_e32 v86, v86
	v_rcp_f32_e32 v87, v87
	v_rcp_f32_e32 v88, v88
	v_rcp_f32_e32 v89, v89
	s_nop 0
	v_cvt_pk_bf16_f32 v164, v82, v83
	v_cvt_pk_bf16_f32 v165, v84, v85
	v_cvt_pk_bf16_f32 v166, v86, v87
	v_cvt_pk_bf16_f32 v167, v88, v89
	v_mul_f32_e32 v90, 0xbfb8aa3b, v90
	v_mul_f32_e32 v91, 0xbfb8aa3b, v91
	v_mul_f32_e32 v92, 0xbfb8aa3b, v92
	v_mul_f32_e32 v93, 0xbfb8aa3b, v93
	v_mul_f32_e32 v94, 0xbfb8aa3b, v94
	v_mul_f32_e32 v95, 0xbfb8aa3b, v95
	v_mul_f32_e32 v96, 0xbfb8aa3b, v96
	v_mul_f32_e32 v97, 0xbfb8aa3b, v97
	v_exp_f32_e32 v90, v90
	v_exp_f32_e32 v91, v91
	v_exp_f32_e32 v92, v92
	v_exp_f32_e32 v93, v93
	v_exp_f32_e32 v94, v94
	v_exp_f32_e32 v95, v95
	v_exp_f32_e32 v96, v96
	v_exp_f32_e32 v97, v97
	v_add_f32_e32 v90, 1.0, v90
	v_add_f32_e32 v91, 1.0, v91
	v_add_f32_e32 v92, 1.0, v92
	v_add_f32_e32 v93, 1.0, v93
	v_add_f32_e32 v94, 1.0, v94
	v_add_f32_e32 v95, 1.0, v95
	v_add_f32_e32 v96, 1.0, v96
	v_add_f32_e32 v97, 1.0, v97
	v_rcp_f32_e32 v90, v90
	v_rcp_f32_e32 v91, v91
	v_rcp_f32_e32 v92, v92
	v_rcp_f32_e32 v93, v93
	v_rcp_f32_e32 v94, v94
	v_rcp_f32_e32 v95, v95
	v_rcp_f32_e32 v96, v96
	v_rcp_f32_e32 v97, v97
	s_nop 0
	v_cvt_pk_bf16_f32 v168, v90, v91
	v_cvt_pk_bf16_f32 v169, v92, v93
	v_cvt_pk_bf16_f32 v170, v94, v95
	v_cvt_pk_bf16_f32 v171, v96, v97
	v_mul_f32_e32 v98, 0xbfb8aa3b, v98
	v_mul_f32_e32 v99, 0xbfb8aa3b, v99
	v_mul_f32_e32 v100, 0xbfb8aa3b, v100
	v_mul_f32_e32 v101, 0xbfb8aa3b, v101
	v_mul_f32_e32 v102, 0xbfb8aa3b, v102
	v_mul_f32_e32 v103, 0xbfb8aa3b, v103
	v_mul_f32_e32 v104, 0xbfb8aa3b, v104
	v_mul_f32_e32 v105, 0xbfb8aa3b, v105
	v_exp_f32_e32 v98, v98
	v_exp_f32_e32 v99, v99
	v_exp_f32_e32 v100, v100
	v_exp_f32_e32 v101, v101
	v_exp_f32_e32 v102, v102
	v_exp_f32_e32 v103, v103
	v_exp_f32_e32 v104, v104
	v_exp_f32_e32 v105, v105
	v_add_f32_e32 v98, 1.0, v98
	v_add_f32_e32 v99, 1.0, v99
	v_add_f32_e32 v100, 1.0, v100
	v_add_f32_e32 v101, 1.0, v101
	v_add_f32_e32 v102, 1.0, v102
	v_add_f32_e32 v103, 1.0, v103
	v_add_f32_e32 v104, 1.0, v104
	v_add_f32_e32 v105, 1.0, v105
	v_rcp_f32_e32 v98, v98
	v_rcp_f32_e32 v99, v99
	v_rcp_f32_e32 v100, v100
	v_rcp_f32_e32 v101, v101
	v_rcp_f32_e32 v102, v102
	v_rcp_f32_e32 v103, v103
	v_rcp_f32_e32 v104, v104
	v_rcp_f32_e32 v105, v105
	s_nop 0
	v_cvt_pk_bf16_f32 v172, v98, v99
	v_cvt_pk_bf16_f32 v173, v100, v101
	v_cvt_pk_bf16_f32 v174, v102, v103
	v_cvt_pk_bf16_f32 v175, v104, v105
	v_mul_f32_e32 v106, 0xbfb8aa3b, v106
	v_mul_f32_e32 v107, 0xbfb8aa3b, v107
	v_mul_f32_e32 v108, 0xbfb8aa3b, v108
	v_mul_f32_e32 v109, 0xbfb8aa3b, v109
	v_mul_f32_e32 v110, 0xbfb8aa3b, v110
	v_mul_f32_e32 v111, 0xbfb8aa3b, v111
	v_mul_f32_e32 v112, 0xbfb8aa3b, v112
	v_mul_f32_e32 v113, 0xbfb8aa3b, v113
; DI unsigned pack2(float a, float b) { f32v2 v = {a, b}; return __builtin_bit_cast(unsigned, __builtin_convertvector(v, bf16v2)); }
; DI float sigm_fast(float x) { return __builtin_amdgcn_rcpf(1.f + __expf(-x)); }
; DI void phase_merge(const Params& p, int l, char* smem, int tid) {
;     ...
; #pragma unroll
;         for (int b2 = 0; b2 < 2; b2++)
; #pragma unroll
;           for (int e = 0; e < 8; e++) sg[b2][e] = pack2(sigm_fast(m[0][b2][2 * e]), sigm_fast(m[0][b2][2 * e + 1]));
;       }
;       f32x16 t[1][2]; zero_acc<1>(t);
;       gemm_main<1>(p.G + (size_t)m0 * 1024 + i * 256, 1024, p.WtBr + ((size_t)l * 4 + i) * 1024 * 256 + (size_t)n0 * 256, 256, 256, t, s, tid);
	v_exp_f32_e32 v106, v106
	v_exp_f32_e32 v107, v107
	v_exp_f32_e32 v108, v108
	v_exp_f32_e32 v109, v109
	v_exp_f32_e32 v110, v110
	v_exp_f32_e32 v111, v111
	v_exp_f32_e32 v112, v112
	v_exp_f32_e32 v113, v113
	v_add_f32_e32 v106, 1.0, v106
	v_add_f32_e32 v107, 1.0, v107
	v_add_f32_e32 v108, 1.0, v108
	v_add_f32_e32 v109, 1.0, v109
	v_add_f32_e32 v110, 1.0, v110
	v_add_f32_e32 v111, 1.0, v111
	v_add_f32_e32 v112, 1.0, v112
	v_add_f32_e32 v113, 1.0, v113
	v_rcp_f32_e32 v106, v106
	v_rcp_f32_e32 v107, v107
	v_rcp_f32_e32 v108, v108
	v_rcp_f32_e32 v109, v109
	v_rcp_f32_e32 v110, v110
	v_rcp_f32_e32 v111, v111
	v_rcp_f32_e32 v112, v112
	v_rcp_f32_e32 v113, v113
	s_nop 0
	v_cvt_pk_bf16_f32 v176, v106, v107
	v_cvt_pk_bf16_f32 v177, v108, v109
	v_cvt_pk_bf16_f32 v178, v110, v111
	v_cvt_pk_bf16_f32 v179, v112, v113
	v_mul_f32_e32 v114, 0xbfb8aa3b, v114
	v_mul_f32_e32 v115, 0xbfb8aa3b, v115
	v_mul_f32_e32 v116, 0xbfb8aa3b, v116
	v_mul_f32_e32 v117, 0xbfb8aa3b, v117
	v_mul_f32_e32 v118, 0xbfb8aa3b, v118
	v_mul_f32_e32 v119, 0xbfb8aa3b, v119
	v_mul_f32_e32 v120, 0xbfb8aa3b, v120
	v_mul_f32_e32 v121, 0xbfb8aa3b, v121
	v_exp_f32_e32 v114, v114
	v_exp_f32_e32 v115, v115
	v_exp_f32_e32 v116, v116
	v_exp_f32_e32 v117, v117
	v_exp_f32_e32 v118, v118
	v_exp_f32_e32 v119, v119
	v_exp_f32_e32 v120, v120
	v_exp_f32_e32 v121, v121
	v_add_f32_e32 v114, 1.0, v114
	v_add_f32_e32 v115, 1.0, v115
	v_add_f32_e32 v116, 1.0, v116
	v_add_f32_e32 v117, 1.0, v117
	v_add_f32_e32 v118, 1.0, v118
	v_add_f32_e32 v119, 1.0, v119
	v_add_f32_e32 v120, 1.0, v120
	v_add_f32_e32 v121, 1.0, v121
	v_rcp_f32_e32 v114, v114
	v_rcp_f32_e32 v115, v115
	v_rcp_f32_e32 v116, v116
	v_rcp_f32_e32 v117, v117
	v_rcp_f32_e32 v118, v118
	v_rcp_f32_e32 v119, v119
	v_rcp_f32_e32 v120, v120
	v_rcp_f32_e32 v121, v121
	s_nop 0
	v_cvt_pk_bf16_f32 v180, v114, v115
	v_cvt_pk_bf16_f32 v181, v116, v117
	v_cvt_pk_bf16_f32 v182, v118, v119
	v_cvt_pk_bf16_f32 v183, v120, v121
	v_mul_f32_e32 v122, 0xbfb8aa3b, v122
	v_mul_f32_e32 v123, 0xbfb8aa3b, v123
	v_mul_f32_e32 v124, 0xbfb8aa3b, v124
	v_mul_f32_e32 v125, 0xbfb8aa3b, v125
	v_mul_f32_e32 v126, 0xbfb8aa3b, v126
	v_mul_f32_e32 v127, 0xbfb8aa3b, v127
	v_mul_f32_e32 v128, 0xbfb8aa3b, v128
	v_mul_f32_e32 v129, 0xbfb8aa3b, v129
	v_exp_f32_e32 v122, v122
	v_exp_f32_e32 v123, v123
	v_exp_f32_e32 v124, v124
	v_exp_f32_e32 v125, v125
	v_exp_f32_e32 v126, v126
	v_exp_f32_e32 v127, v127
	v_exp_f32_e32 v128, v128
	v_exp_f32_e32 v129, v129
	v_add_f32_e32 v122, 1.0, v122
	v_add_f32_e32 v123, 1.0, v123
	v_add_f32_e32 v124, 1.0, v124
	v_add_f32_e32 v125, 1.0, v125
	v_add_f32_e32 v126, 1.0, v126
	v_add_f32_e32 v127, 1.0, v127
	v_add_f32_e32 v128, 1.0, v128
	v_add_f32_e32 v129, 1.0, v129
	v_rcp_f32_e32 v122, v122
	v_rcp_f32_e32 v123, v123
	v_rcp_f32_e32 v124, v124
	v_rcp_f32_e32 v125, v125
	v_rcp_f32_e32 v126, v126
	v_rcp_f32_e32 v127, v127
	v_rcp_f32_e32 v128, v128
	v_rcp_f32_e32 v129, v129
	s_nop 0
	v_cvt_pk_bf16_f32 v184, v122, v123
	v_cvt_pk_bf16_f32 v185, v124, v125
	v_cvt_pk_bf16_f32 v186, v126, v127
	v_cvt_pk_bf16_f32 v187, v128, v129
	s_add_u32 s13, s13, 1
	v_mov_b32_e32 v66, 0
	v_mov_b32_e32 v67, 0
	v_mov_b32_e32 v68, 0
	v_mov_b32_e32 v69, 0
	v_mov_b32_e32 v70, 0
	v_mov_b32_e32 v71, 0
	v_mov_b32_e32 v72, 0
	v_mov_b32_e32 v73, 0
	v_mov_b32_e32 v74, 0
	v_mov_b32_e32 v75, 0
	v_mov_b32_e32 v76, 0
	v_mov_b32_e32 v77, 0
	v_mov_b32_e32 v78, 0
	v_mov_b32_e32 v79, 0
	v_mov_b32_e32 v80, 0
	v_mov_b32_e32 v81, 0
	v_mov_b32_e32 v82, 0
	v_mov_b32_e32 v83, 0
	v_mov_b32_e32 v84, 0
	v_mov_b32_e32 v85, 0
	v_mov_b32_e32 v86, 0
	v_mov_b32_e32 v87, 0
	v_mov_b32_e32 v88, 0
	v_mov_b32_e32 v89, 0
	v_mov_b32_e32 v90, 0
	v_mov_b32_e32 v91, 0
	v_mov_b32_e32 v92, 0
	v_mov_b32_e32 v93, 0
	v_mov_b32_e32 v94, 0
	v_mov_b32_e32 v95, 0
	v_mov_b32_e32 v96, 0
	v_mov_b32_e32 v97, 0
	v_mov_b32_e32 v98, 0
	v_mov_b32_e32 v99, 0
	v_mov_b32_e32 v100, 0
	v_mov_b32_e32 v101, 0
	v_mov_b32_e32 v102, 0
	v_mov_b32_e32 v103, 0
	v_mov_b32_e32 v104, 0
	v_mov_b32_e32 v105, 0
	v_mov_b32_e32 v106, 0
	v_mov_b32_e32 v107, 0
	v_mov_b32_e32 v108, 0
	v_mov_b32_e32 v109, 0
	v_mov_b32_e32 v110, 0
	v_mov_b32_e32 v111, 0
	v_mov_b32_e32 v112, 0
	v_mov_b32_e32 v113, 0
	v_mov_b32_e32 v114, 0
	v_mov_b32_e32 v115, 0
	v_mov_b32_e32 v116, 0
	v_mov_b32_e32 v117, 0
	v_mov_b32_e32 v118, 0
	v_mov_b32_e32 v119, 0
	v_mov_b32_e32 v120, 0
	v_mov_b32_e32 v121, 0
	v_mov_b32_e32 v122, 0
	v_mov_b32_e32 v123, 0
	v_mov_b32_e32 v124, 0
	v_mov_b32_e32 v125, 0
	v_mov_b32_e32 v126, 0
	v_mov_b32_e32 v127, 0
	v_mov_b32_e32 v128, 0
	v_mov_b32_e32 v129, 0
	s_waitcnt vmcnt(0) lgkmcnt(0)
	s_barrier
	ds_read_b128 v[224:227], v138 offset:0
	ds_read_b128 v[232:235], v142 offset:0
	ds_read_b128 v[228:231], v138 offset:4096
	ds_read_b128 v[236:239], v142 offset:4096
	s_add_u32 m0, s10, 0xc000
	s_nop 0
	global_load_lds_dwordx4 v130, s[8:9]
	s_add_u32 m0, s10, 0xc400
	s_nop 0
	global_load_lds_dwordx4 v131, s[8:9]
	s_add_u32 m0, s10, 0xc800
	s_nop 0
	global_load_lds_dwordx4 v132, s[8:9]
	s_add_u32 m0, s10, 0xcc00
	s_nop 0
	global_load_lds_dwordx4 v133, s[8:9]
	s_add_u32 s8, s8, 128
	s_addc_u32 s9, s9, 0
	s_mov_b32 s11, 1
; #define G_STORE(S, bf) { *(uint4*)&s->a[bf][srow][skc] = S##a0; *(uint4*)&s->a[bf][srow + 32][skc] = S##a1; \
;     if (MB == 2) { *(uint4*)&s->a[bf][srow + 64][skc] = S##a2; *(uint4*)&s->a[bf][srow + 96][skc] = S##a3; } \
;     *(uint4*)&s->b[bf][srow][skc] = S##b0; *(uint4*)&s->b[bf][srow + 32][skc] = S##b1; *(uint4*)&s->b[bf][srow + 64][skc] = S##b2; *(uint4*)&s->b[bf][srow + 96][skc] = S##b3; }
; template <int MB, bool PF2 = true>
; DI void gemm_main(const u16* __restrict__ A, int lda, const u16* __restrict__ B, int ldb, int K, f32x16 (&acc)[MB][2], GemmLds* s, int tid) {
;     ...
;   for (int kt = 0; kt < KT; kt += 2) {
;     { const int k2 = min((kt + 2) * 64, klast); G_LOAD(q, k2); }
;     __builtin_amdgcn_sched_barrier(0);
;     G_COMPUTE(0);
;     G_STORE(p, 1);
;     __syncthreads();
;     { const int k3 = min((kt + 3) * 64, klast); G_LOAD(p, k3); }
;     __builtin_amdgcn_sched_barrier(0);
;     G_COMPUTE(1);
;     G_STORE(q, 0);
;     __syncthreads();
;   }
.Lmgt_loop:
	ds_read_b128 v[240:243], v139 offset:0
	ds_read_b128 v[192:195], v143 offset:0
	ds_read_b128 v[188:191], v139 offset:4096
	ds_read_b128 v[196:199], v143 offset:4096
	s_waitcnt lgkmcnt(4)
	s_add_u32 m0, s10, 0x8000
	v_mfma_f32_32x32x16_bf16 v[66:81], v[232:235], v[224:227], v[66:81]
	global_load_lds_dwordx4 v200, s[4:5]
	s_add_u32 m0, s10, 0x8400
	v_mfma_f32_32x32x16_bf16 v[82:97], v[236:239], v[224:227], v[82:97]
	global_load_lds_dwordx4 v201, s[4:5]
	s_add_u32 m0, s10, 0x8800
	v_mfma_f32_32x32x16_bf16 v[98:113], v[232:235], v[228:231], v[98:113]
	global_load_lds_dwordx4 v202, s[4:5]
	s_add_u32 m0, s10, 0x8c00
	v_mfma_f32_32x32x16_bf16 v[114:129], v[236:239], v[228:231], v[114:129]
	global_load_lds_dwordx4 v203, s[4:5]
	s_add_u32 s4, s4, 128
	s_addc_u32 s5, s5, 0
	ds_read_b128 v[224:227], v140 offset:0
	ds_read_b128 v[232:235], v144 offset:0
	ds_read_b128 v[228:231], v140 offset:4096
	ds_read_b128 v[236:239], v144 offset:4096
	s_waitcnt lgkmcnt(4)
	v_mfma_f32_32x32x16_bf16 v[66:81], v[192:195], v[240:243], v[66:81]
	v_mfma_f32_32x32x16_bf16 v[82:97], v[196:199], v[240:243], v[82:97]
	v_mfma_f32_32x32x16_bf16 v[98:113], v[192:195], v[188:191], v[98:113]
	v_mfma_f32_32x32x16_bf16 v[114:129], v[196:199], v[188:191], v[114:129]
	ds_read_b128 v[240:243], v141 offset:0
	ds_read_b128 v[192:195], v145 offset:0
	ds_read_b128 v[188:191], v141 offset:4096
	ds_read_b128 v[196:199], v145 offset:4096
	s_waitcnt lgkmcnt(4)
	v_mfma_f32_32x32x16_bf16 v[66:81], v[232:235], v[224:227], v[66:81]
	v_mfma_f32_32x32x16_bf16 v[82:97], v[236:239], v[224:227], v[82:97]
	v_mfma_f32_32x32x16_bf16 v[98:113], v[232:235], v[228:231], v[98:113]
	v_mfma_f32_32x32x16_bf16 v[114:129], v[236:239], v[228:231], v[114:129]
	s_waitcnt vmcnt(0) lgkmcnt(0)
	s_barrier
	ds_read_b128 v[224:227], v138 offset:32768
	ds_read_b128 v[232:235], v142 offset:32768
	ds_read_b128 v[228:231], v138 offset:36864
	ds_read_b128 v[236:239], v142 offset:36864
	s_cmp_eq_u32 s11, 0
	s_cbranch_scc1 .Lmgt_hold0
	s_add_u32 m0, s10, 0x4000
	v_mfma_f32_32x32x16_bf16 v[66:81], v[192:195], v[240:243], v[66:81]
	global_load_lds_dwordx4 v130, s[8:9]
	s_add_u32 m0, s10, 0x4400
	v_mfma_f32_32x32x16_bf16 v[82:97], v[196:199], v[240:243], v[82:97]
	global_load_lds_dwordx4 v131, s[8:9]
	s_add_u32 m0, s10, 0x4800
	v_mfma_f32_32x32x16_bf16 v[98:113], v[192:195], v[188:191], v[98:113]
	global_load_lds_dwordx4 v132, s[8:9]
	s_add_u32 m0, s10, 0x4c00
	v_mfma_f32_32x32x16_bf16 v[114:129], v[196:199], v[188:191], v[114:129]
	global_load_lds_dwordx4 v133, s[8:9]
	s_add_u32 s8, s8, 128
	s_addc_u32 s9, s9, 0
	s_branch .Lmgt_held0

; #define G_STORE(S, bf) { *(uint4*)&s->a[bf][srow][skc] = S##a0; *(uint4*)&s->a[bf][srow + 32][skc] = S##a1; \
;     if (MB == 2) { *(uint4*)&s->a[bf][srow + 64][skc] = S##a2; *(uint4*)&s->a[bf][srow + 96][skc] = S##a3; } \
;     *(uint4*)&s->b[bf][srow][skc] = S##b0; *(uint4*)&s->b[bf][srow + 32][skc] = S##b1; *(uint4*)&s->b[bf][srow + 64][skc] = S##b2; *(uint4*)&s->b[bf][srow + 96][skc] = S##b3; }
; template <int MB, bool PF2 = true>
; DI void gemm_main(const u16* __restrict__ A, int lda, const u16* __restrict__ B, int ldb, int K, f32x16 (&acc)[MB][2], GemmLds* s, int tid) {
;     ...
;   for (int kt = 0; kt < KT; kt += 2) {
;     { const int k2 = min((kt + 2) * 64, klast); G_LOAD(q, k2); }
;     __builtin_amdgcn_sched_barrier(0);
;     G_COMPUTE(0);
;     G_STORE(p, 1);
;     __syncthreads();
;     { const int k3 = min((kt + 3) * 64, klast); G_LOAD(p, k3); }
;     __builtin_amdgcn_sched_barrier(0);
;     G_COMPUTE(1);
;     G_STORE(q, 0);
;     __syncthreads();
;   }
; DI void phase_merge(const Params& p, int l, char* smem, int tid) {
;     ...
;     for (int i = 0; i < 4; i++) {
;       if ((ZERO_MASK >> i) & 1) continue;
;       unsigned sg[2][8];
;       {
;         f32x16 m[1][2]; zero_acc<1>(m);
;         gemm_main<1>(p.xn + (size_t)m0 * 1024, 1024, p.WtM + (size_t)l * 4096 * 1024 + ((size_t)i * 1024 + n0) * 1024, 1024, 1024, m, s, tid);
.Lmgt_held0:
	s_cmp_eq_u32 s11, 0
	s_cbranch_scc1 .Lmgt_last
	ds_read_b128 v[240:243], v139 offset:32768
	ds_read_b128 v[192:195], v143 offset:32768
	ds_read_b128 v[188:191], v139 offset:36864
	ds_read_b128 v[196:199], v143 offset:36864
	s_waitcnt lgkmcnt(4)
	s_add_u32 m0, s10, 0x0
	v_mfma_f32_32x32x16_bf16 v[66:81], v[232:235], v[224:227], v[66:81]
	global_load_lds_dwordx4 v200, s[4:5]
	s_add_u32 m0, s10, 0x400
	v_mfma_f32_32x32x16_bf16 v[82:97], v[236:239], v[224:227], v[82:97]
	global_load_lds_dwordx4 v201, s[4:5]
	s_add_u32 m0, s10, 0x800
	v_mfma_f32_32x32x16_bf16 v[98:113], v[232:235], v[228:231], v[98:113]
	global_load_lds_dwordx4 v202, s[4:5]
	s_add_u32 m0, s10, 0xc00
	v_mfma_f32_32x32x16_bf16 v[114:129], v[236:239], v[228:231], v[114:129]
	global_load_lds_dwordx4 v203, s[4:5]
	s_add_u32 s4, s4, 128
	s_addc_u32 s5, s5, 0
	ds_read_b128 v[224:227], v140 offset:32768
	ds_read_b128 v[232:235], v144 offset:32768
	ds_read_b128 v[228:231], v140 offset:36864
	ds_read_b128 v[236:239], v144 offset:36864
	s_waitcnt lgkmcnt(4)
	v_mfma_f32_32x32x16_bf16 v[66:81], v[192:195], v[240:243], v[66:81]
	v_mfma_f32_32x32x16_bf16 v[82:97], v[196:199], v[240:243], v[82:97]
	v_mfma_f32_32x32x16_bf16 v[98:113], v[192:195], v[188:191], v[98:113]
	v_mfma_f32_32x32x16_bf16 v[114:129], v[196:199], v[188:191], v[114:129]
	ds_read_b128 v[240:243], v141 offset:32768
	ds_read_b128 v[192:195], v145 offset:32768
	ds_read_b128 v[188:191], v141 offset:36864
	ds_read_b128 v[196:199], v145 offset:36864
	s_waitcnt lgkmcnt(4)
	v_mfma_f32_32x32x16_bf16 v[66:81], v[232:235], v[224:227], v[66:81]
	v_mfma_f32_32x32x16_bf16 v[82:97], v[236:239], v[224:227], v[82:97]
	v_mfma_f32_32x32x16_bf16 v[98:113], v[232:235], v[228:231], v[98:113]
	v_mfma_f32_32x32x16_bf16 v[114:129], v[236:239], v[228:231], v[114:129]
	s_waitcnt vmcnt(0) lgkmcnt(0)
	s_barrier
	ds_read_b128 v[224:227], v138 offset:0
	ds_read_b128 v[232:235], v142 offset:0
	ds_read_b128 v[228:231], v138 offset:4096
	ds_read_b128 v[236:239], v142 offset:4096
	s_add_u32 m0, s10, 0xc000
	v_mfma_f32_32x32x16_bf16 v[66:81], v[192:195], v[240:243], v[66:81]
	global_load_lds_dwordx4 v130, s[8:9]
	s_add_u32 m0, s10, 0xc400
	v_mfma_f32_32x32x16_bf16 v[82:97], v[196:199], v[240:243], v[82:97]
	global_load_lds_dwordx4 v131, s[8:9]
	s_add_u32 m0, s10, 0xc800
	v_mfma_f32_32x32x16_bf16 v[98:113], v[192:195], v[188:191], v[98:113]
	global_load_lds_dwordx4 v132, s[8:9]
	s_add_u32 m0, s10, 0xcc00
	v_mfma_f32_32x32x16_bf16 v[114:129], v[196:199], v[188:191], v[114:129]
	global_load_lds_dwordx4 v133, s[8:9]
	s_add_u32 s8, s8, 128
	s_addc_u32 s9, s9, 0
	s_sub_u32 s11, s11, 1
	s_branch .Lmgt_loop
.Lmgt_last:
	s_cmp_eq_u32 s13, 7
	s_cbranch_scc1 .Lmgt_nopf
	s_add_u32 s6, s13, 1
	s_lshr_b32 s6, s6, 1
	s_mov_b32 s4, s2
	s_mov_b32 s5, s3
	s_lshl_b32 s7, s6, 21
	s_add_u32 s7, s7, s19
	s_add_u32 s8, s14, s7
	s_addc_u32 s9, s15, 0
	ds_read_b128 v[240:243], v139 offset:32768
	ds_read_b128 v[192:195], v143 offset:32768
	ds_read_b128 v[188:191], v139 offset:36864
	ds_read_b128 v[196:199], v143 offset:36864
	s_waitcnt lgkmcnt(4)
	s_add_u32 m0, s10, 0x4000
	v_mfma_f32_32x32x16_bf16 v[66:81], v[232:235], v[224:227], v[66:81]
	global_load_lds_dwordx4 v200, s[8:9]
	s_add_u32 m0, s10, 0x4400
	v_mfma_f32_32x32x16_bf16 v[82:97], v[236:239], v[224:227], v[82:97]
	global_load_lds_dwordx4 v201, s[8:9]
	s_add_u32 m0, s10, 0x4800
	v_mfma_f32_32x32x16_bf16 v[98:113], v[232:235], v[228:231], v[98:113]
	global_load_lds_dwordx4 v202, s[8:9]
	s_add_u32 m0, s10, 0x4c00
	v_mfma_f32_32x32x16_bf16 v[114:129], v[236:239], v[228:231], v[114:129]
	global_load_lds_dwordx4 v203, s[8:9]
	s_add_u32 s8, s8, 128
	s_addc_u32 s9, s9, 0
	ds_read_b128 v[224:227], v140 offset:32768
	ds_read_b128 v[232:235], v144 offset:32768
	ds_read_b128 v[228:231], v140 offset:36864
	ds_read_b128 v[236:239], v144 offset:36864
	s_waitcnt lgkmcnt(4)
	s_add_u32 m0, s10, 0x0
	v_mfma_f32_32x32x16_bf16 v[66:81], v[192:195], v[240:243], v[66:81]
	global_load_lds_dwordx4 v200, s[4:5]
	s_add_u32 m0, s10, 0x400
	v_mfma_f32_32x32x16_bf16 v[82:97], v[196:199], v[240:243], v[82:97]
	global_load_lds_dwordx4 v201, s[4:5]
	s_add_u32 m0, s10, 0x800
	v_mfma_f32_32x32x16_bf16 v[98:113], v[192:195], v[188:191], v[98:113]
	global_load_lds_dwordx4 v202, s[4:5]
	s_add_u32 m0, s10, 0xc00
	v_mfma_f32_32x32x16_bf16 v[114:129], v[196:199], v[188:191], v[114:129]
	global_load_lds_dwordx4 v203, s[4:5]
	s_add_u32 s4, s4, 128
	s_addc_u32 s5, s5, 0
	ds_read_b128 v[240:243], v141 offset:32768
	ds_read_b128 v[192:195], v145 offset:32768
	ds_read_b128 v[188:191], v141 offset:36864
	ds_read_b128 v[196:199], v145 offset:36864
	s_waitcnt lgkmcnt(4)
	v_mfma_f32_32x32x16_bf16 v[66:81], v[232:235], v[224:227], v[66:81]
	v_mfma_f32_32x32x16_bf16 v[82:97], v[236:239], v[224:227], v[82:97]
	v_mfma_f32_32x32x16_bf16 v[98:113], v[232:235], v[228:231], v[98:113]
	v_mfma_f32_32x32x16_bf16 v[114:129], v[236:239], v[228:231], v[114:129]
	s_waitcnt lgkmcnt(0)
	s_barrier
	v_mfma_f32_32x32x16_bf16 v[66:81], v[192:195], v[240:243], v[66:81]
	v_mfma_f32_32x32x16_bf16 v[82:97], v[196:199], v[240:243], v[82:97]
	v_mfma_f32_32x32x16_bf16 v[98:113], v[192:195], v[188:191], v[98:113]
	v_mfma_f32_32x32x16_bf16 v[114:129], v[196:199], v[188:191], v[114:129]
	s_branch .Lmgt_kdone
